# baseline (speedup 1.0000x reference)
; template <int MODE>
; __device__ __forceinline__ void attn_item(const Params& P, int b, int h, int qb, char* lds) {
;     ...
;         const float nref = -m_reg;
; #pragma unroll
;         for (int r = 0; r < 16; ++r) { p0[r] = nref; p1[r] = nref; }
;       }
;       {
;         const char* kbp = K_lds + buf * 16384;
; #pragma unroll
;         for (int d0 = 0; d0 < 8; ++d0) {
;           const char* a = kbp + KSWZ(r32, (d0 * 16 + hi * 8) * 2);
;           const bf16x8 b0 = *(const bf16x8*)a;
;           const bf16x8 b1 = *(const bf16x8*)(a + 32 * 256);
;           p0 = __builtin_amdgcn_mfma_f32_32x32x16_bf16(b0, qr[d0], p0, 0, 0, 0);
;           p1 = __builtin_amdgcn_mfma_f32_32x32x16_bf16(b1, qr[d0], p1, 0, 0, 0);
;         }
;       }
;       const float NEG = -__builtin_inff();
;       if (MODE == 0) {
;       } else {
;         if (kb + 63 > q0) {
;           const int dq = qpos - kb - 4 * hi;
; #pragma unroll
;           for (int r = 0; r < 16; ++r) {
;             const int c = (r & 3) + 8 * (r >> 2);
;             if (dq - c < 0) p0[r] = NEG;
;             if (dq - c - 32 < 0) p1[r] = NEG;
;           }
;         }
;       }
;       float pmax = p0[0];
; #pragma unroll
;       for (int r = 1; r < 16; ++r) pmax = fmaxf(pmax, p0[r]);
; #pragma unroll
;       for (int r = 0; r < 16; ++r) pmax = fmaxf(pmax, p1[r]);
;       pmax = fmaxf(pmax, __shfl_xor(pmax, 32));
;       if (!(started && __all(pmax < -160.f))) {
;       float alpha = 1.f;
;       if (!started || __any(pmax > 6.f)) {
.Lmy_pr_a:
	v_add_u32_e32 v0, s9, v182
	v_add_u32_e32 v6, v0, v183
	v_add_u32_e32 v10, v0, v181
	ds_read_b128 v[212:215], v6 offset:32768
	ds_read_b128 v[6:9], v6 offset:40960
	v_add_u32_e32 v187, v0, v179
	ds_read_b128 v[216:219], v10 offset:32768
	ds_read_b128 v[10:13], v10 offset:40960
	v_add_u32_e32 v2, v0, v178
	ds_read_b128 v[220:223], v187 offset:32768
	ds_read_b128 v[188:191], v187 offset:40960
	v_add_u32_e32 v196, v0, v177
	ds_read_b128 v[224:227], v2 offset:32768
	ds_read_b128 v[192:195], v2 offset:40960
	v_add_u32_e32 v3, v0, v176
	ds_read_b128 v[228:231], v196 offset:32768
	ds_read_b128 v[196:199], v196 offset:40960
	v_add_u32_e32 v204, v0, v175
	ds_read_b128 v[232:235], v3 offset:32768
	ds_read_b128 v[200:203], v3 offset:40960
	ds_read_b128 v[236:239], v204 offset:32768
	ds_read_b128 v[204:207], v204 offset:40960
	v_add_u32_e32 v0, v0, v174
	v_xor_b32_e32 v96, 0x80000000, v186
	v_mov_b32_e32 v97, v96
	v_mov_b32_e32 v98, v96
	v_mov_b32_e32 v99, v96
	v_mov_b32_e32 v100, v96
	v_mov_b32_e32 v101, v96
	v_mov_b32_e32 v102, v96
	v_mov_b32_e32 v103, v96
	v_mov_b32_e32 v104, v96
	v_mov_b32_e32 v105, v96
	v_mov_b32_e32 v106, v96
	v_mov_b32_e32 v107, v96
	v_mov_b32_e32 v108, v96
	v_mov_b32_e32 v109, v96
	v_mov_b32_e32 v110, v96
	v_mov_b32_e32 v111, v96
	s_cmp_eq_u32 s0, 0
	s_cselect_b64 s[10:11], -1, 0
	s_cmp_lg_u32 s0, 0
	s_waitcnt lgkmcnt(13)
	v_mfma_f32_32x32x16_bf16 v[112:127], v[212:215], v[156:159], v[96:111]
	ds_read_b128 v[240:243], v0 offset:32768
	ds_read_b128 v[208:211], v0 offset:40960
	s_waitcnt lgkmcnt(14)
	v_mfma_f32_32x32x16_bf16 v[96:111], v[6:9], v[156:159], v[96:111]
	s_waitcnt lgkmcnt(13)
	v_mfma_f32_32x32x16_bf16 v[112:127], v[216:219], v[152:155], v[112:127]
	s_waitcnt lgkmcnt(12)
	v_mfma_f32_32x32x16_bf16 v[96:111], v[10:13], v[152:155], v[96:111]
	s_waitcnt lgkmcnt(11)
	v_mfma_f32_32x32x16_bf16 v[112:127], v[220:223], v[148:151], v[112:127]
	s_waitcnt lgkmcnt(10)
	v_mfma_f32_32x32x16_bf16 v[96:111], v[188:191], v[148:151], v[96:111]
	s_waitcnt lgkmcnt(9)
	v_mfma_f32_32x32x16_bf16 v[112:127], v[224:227], v[144:147], v[112:127]
	s_waitcnt lgkmcnt(8)
	v_mfma_f32_32x32x16_bf16 v[96:111], v[192:195], v[144:147], v[96:111]
	s_waitcnt lgkmcnt(7)
	v_mfma_f32_32x32x16_bf16 v[112:127], v[228:231], v[140:143], v[112:127]
	s_waitcnt lgkmcnt(6)
	v_mfma_f32_32x32x16_bf16 v[96:111], v[196:199], v[140:143], v[96:111]
	s_waitcnt lgkmcnt(5)
	v_mfma_f32_32x32x16_bf16 v[112:127], v[232:235], v[136:139], v[112:127]
	s_waitcnt lgkmcnt(4)
	v_mfma_f32_32x32x16_bf16 v[96:111], v[200:203], v[136:139], v[96:111]
	s_waitcnt lgkmcnt(3)
	v_mfma_f32_32x32x16_bf16 v[112:127], v[236:239], v[132:135], v[112:127]
	s_waitcnt lgkmcnt(2)
	v_mfma_f32_32x32x16_bf16 v[96:111], v[204:207], v[132:135], v[96:111]
	s_waitcnt lgkmcnt(1)
	v_mfma_f32_32x32x16_bf16 v[112:127], v[240:243], v[128:131], v[112:127]
	s_waitcnt lgkmcnt(0)
	v_mfma_f32_32x32x16_bf16 v[96:111], v[208:211], v[128:131], v[96:111]
	s_nop 10
	v_max_f32_e32 v0, v112, v113
	v_max3_f32 v0, v0, v114, v115
	v_max3_f32 v0, v0, v116, v117
	v_max3_f32 v0, v0, v118, v119
	v_max3_f32 v0, v0, v120, v121
	v_max3_f32 v0, v0, v122, v123
	v_max3_f32 v0, v0, v124, v125
	v_max3_f32 v0, v0, v126, v127
	v_max3_f32 v0, v0, v96, v97
	v_max3_f32 v0, v0, v98, v99
	v_max3_f32 v0, v0, v100, v101
	v_max3_f32 v0, v0, v102, v103
	v_max3_f32 v0, v0, v104, v105
	v_max3_f32 v0, v0, v106, v107
	v_max3_f32 v0, v0, v108, v109
	v_max3_f32 v0, v0, v110, v111
	v_mov_b32_e32 v2, v0
	s_nop 1
	v_permlane32_swap_b32_e32 v0, v2
	v_max_f32_e32 v0, v0, v2
	s_cbranch_scc0 .LBB0_689
	v_cmp_gt_f32_e32 vcc, s45, v0
	s_mov_b64 s[36:37], 0
	s_cmp_lg_u64 vcc, exec
	s_mov_b64 s[34:35], 0
	s_mov_b64 s[38:39], 0
	s_cbranch_scc0 .LBB0_690
	v_cmp_lt_f32_e32 vcc, s46, v0
	s_cbranch_vccz .Lmy_fast0
	v_max_f32_e32 v2, v0, v0
	v_max_f32_e32 v2, 0, v2
	s_mov_b64 s[38:39], -1
	s_and_b64 vcc, exec, s[36:37]
	s_cbranch_vccnz .LBB0_691

; template <int MODE>
; __device__ __forceinline__ void attn_item(const Params& P, int b, int h, int qb, char* lds) {
;     ...
;       float pmax = p0[0];
; #pragma unroll
;       for (int r = 1; r < 16; ++r) pmax = fmaxf(pmax, p0[r]);
; #pragma unroll
;       for (int r = 0; r < 16; ++r) pmax = fmaxf(pmax, p1[r]);
;       pmax = fmaxf(pmax, __shfl_xor(pmax, 32));
;       if (!(started && __all(pmax < -160.f))) {
;       float alpha = 1.f;
;       if (!started || __any(pmax > 6.f)) {
.LBB0_1027:
	s_nop 9
	v_max_f32_e32 v0, v96, v97
	v_max3_f32 v0, v0, v98, v99
	v_max3_f32 v0, v0, v100, v101
	v_max3_f32 v0, v0, v102, v103
	v_max3_f32 v0, v0, v104, v105
	v_max3_f32 v0, v0, v106, v107
	v_max3_f32 v0, v0, v108, v109
	v_max3_f32 v0, v0, v110, v111
	v_max3_f32 v0, v0, v112, v113
	v_max3_f32 v0, v0, v114, v115
	v_max3_f32 v0, v0, v116, v117
	v_max3_f32 v0, v0, v118, v119
	v_max3_f32 v0, v0, v120, v121
	v_max3_f32 v0, v0, v122, v123
	v_max3_f32 v0, v0, v124, v125
	v_max3_f32 v0, v0, v126, v127
	v_mov_b32_e32 v2, v0
	s_nop 1
	v_permlane32_swap_b32_e32 v0, v2
	s_cmp_eq_u32 s38, 0
	s_cselect_b64 s[10:11], -1, 0
	s_cmp_lg_u32 s38, 0
	v_max_f32_e32 v0, v0, v2
	s_cbranch_scc0 .LBB0_1033
	v_cmp_gt_f32_e32 vcc, s59, v0
	s_mov_b64 s[40:41], 0
	s_cmp_lg_u64 vcc, exec
	s_mov_b64 s[38:39], 0
	s_mov_b64 s[42:43], 0
	s_cbranch_scc0 .LBB0_1034
	v_cmp_lt_f32_e32 vcc, s60, v0
	s_cbranch_vccz .Lmy_fast1
	v_max_f32_e32 v2, v0, v0
	v_max_f32_e32 v2, 0, v2
	s_mov_b64 s[42:43], -1
	s_and_b64 vcc, exec, s[40:41]
	s_cbranch_vccnz .LBB0_1035
